# half of the workgroups (bit 3 of workgroup id) run the HGRN/S5 output passes before their attention units instead of after, so low-power passes overlap attention
# speedup vs baseline: 1.0153x; 1.0153x over previous
_Z9hymba_fwd4Args:
	s_mov_b32 s100, 0
	v_and_b32_e32 v18, 0x3ff, v0
	s_mov_b64 s[84:85], s[0:1]
	v_cmp_eq_u32_e32 vcc, 0, v18
	s_and_saveexec_b64 s[4:5], vcc
	v_mov_b32_e32 v2, 0
	v_mov_b32_e32 v3, v2
	v_mov_b32_e32 v4, v2
	v_mov_b32_e32 v5, v2
	ds_write_b128 v2, v[2:5] offset:256
	s_or_b64 exec, exec, s[4:5]
	v_cmp_gt_u32_e32 vcc, 4, v18
	s_and_saveexec_b64 s[4:5], vcc
	v_lshlrev_b32_e32 v1, 2, v18
	v_mov_b32_e32 v2, 0
	ds_write_b32 v1, v2 offset:272
	s_or_b64 exec, exec, s[4:5]
	v_and_b32_e32 v1, 63, v18
	v_cmp_eq_u32_e32 vcc, 0, v1
	s_waitcnt lgkmcnt(0)
	s_barrier
	s_and_saveexec_b64 s[4:5], vcc
	s_cbranch_execz .LBB0_8
	s_mov_b64 s[8:9], exec
	v_mbcnt_lo_u32_b32 v1, s8, 0
	v_mbcnt_hi_u32_b32 v1, s9, v1
	s_getreg_b32 s0, hwreg(HW_REG_HW_ID, 0, 7)
	v_cmp_eq_u32_e32 vcc, 0, v1
	s_and_saveexec_b64 s[6:7], vcc
	s_cbranch_execz .LBB0_7
	s_lshr_b32 s0, s0, 2
	s_and_b32 s0, s0, 12
	s_bcnt1_i32_b64 s1, s[8:9]
	v_mov_b32_e32 v2, s0
	v_mov_b32_e32 v3, s1
	ds_add_rtn_u32 v2, v2, v3 offset:272

.Lord_att:
	s_mov_b64 s[10:11], s[84:85]
	s_waitcnt lgkmcnt(0)
	v_mov_b32_e32 v0, v173
	s_barrier
	s_getreg_b32 s1, hwreg(HW_REG_HW_ID, 0, 7)
	s_and_b32 s1, s1, 63
	s_lshl_b32 s1, s1, 2
	v_mov_b32_e32 v1, s1
	ds_read_b32 v6, v1
	s_load_dwordx8 s[12:19], s[10:11], 0x90
	v_and_b32_e32 v1, 63, v0
	s_lshl_b32 s66, s70, 6
	v_or_b32_e32 v160, s66, v1
	v_lshlrev_b64 v[2:3], 2, v[160:161]
	s_waitcnt lgkmcnt(0)
	v_lshl_add_u64 v[4:5], s[12:13], 0, v[2:3]
	global_load_dword v7, v[4:5], off
	v_lshl_add_u64 v[4:5], s[14:15], 0, v[2:3]
	global_load_dword v8, v[4:5], off
	v_lshl_add_u64 v[4:5], s[16:17], 0, v[2:3]
	v_lshl_add_u64 v[2:3], s[18:19], 0, v[2:3]
	global_load_dword v4, v[4:5], off
	v_readfirstlane_b32 s1, v6
	global_load_dword v2, v[2:3], off
	s_load_dwordx2 s[12:13], s[10:11], 0xb0
	s_getreg_b32 s6, hwreg(HW_REG_HW_ID, 0, 7)
	s_and_b32 s6, s6, 63
	s_lshl_b32 s6, s6, 2
	s_lshl_b32 s1, s1, 6
	s_and_b32 s1, s1, 0x3fc0
	s_waitcnt vmcnt(2)
	v_mul_f32_e32 v3, v7, v8
	ds_bpermute_b32 v3, v176, v3
	s_waitcnt vmcnt(0)
	v_mul_f32_e32 v5, v4, v2
	ds_bpermute_b32 v5, v176, v5
	s_waitcnt lgkmcnt(0)
	v_fmac_f32_e32 v3, v7, v8
	v_mov_b32_e32 v7, s6
	v_readlane_b32 s6, v255, 12
	v_readlane_b32 s7, v255, 13
	v_fmac_f32_e32 v5, v4, v2
	ds_bpermute_b32 v2, v177, v3
	ds_bpermute_b32 v4, v177, v5
	s_and_b64 vcc, exec, s[6:7]
	s_waitcnt lgkmcnt(1)
	v_add_f32_e32 v2, v3, v2
	s_waitcnt lgkmcnt(0)
	v_add_f32_e32 v3, v5, v4
	ds_bpermute_b32 v4, v178, v2
	ds_bpermute_b32 v5, v178, v3
	s_waitcnt lgkmcnt(1)
	v_add_f32_e32 v2, v2, v4
	s_waitcnt lgkmcnt(0)
	v_add_f32_e32 v3, v3, v5
	ds_bpermute_b32 v4, v179, v2
	ds_bpermute_b32 v5, v179, v3
	s_waitcnt lgkmcnt(1)
	v_add_f32_e32 v2, v2, v4
	s_waitcnt lgkmcnt(0)
	v_add_f32_e32 v3, v3, v5
	ds_bpermute_b32 v4, v180, v2
	ds_bpermute_b32 v6, v180, v3
	s_waitcnt lgkmcnt(1)
	v_add_f32_e32 v5, v2, v4
	s_waitcnt lgkmcnt(0)
	v_add_f32_e32 v3, v3, v6
	ds_bpermute_b32 v6, v181, v5
	ds_bpermute_b32 v4, v181, v3
	ds_read_b32 v2, v7
	s_waitcnt lgkmcnt(0)
	v_add_u32_e32 v2, s1, v0
	s_nop 0
	v_readfirstlane_b32 s1, v2
	s_cbranch_vccnz .LBB0_423
	s_cmp_eq_u32 s100, 1
	s_cbranch_scc1 .Lord_go
	s_bitcmp1_b32 s2, 3
	s_cbranch_scc0 .Lord_go
	s_mov_b32 s100, 2
	s_branch .LBB0_423
.Lord_go:
	v_cvt_f32_u32_e32 v7, s70
	s_mov_b32 s8, 0x3fb8aa3b
	s_load_dwordx2 s[42:43], s[10:11], 0xe0
	v_add_f32_e32 v5, v5, v6
	v_mul_f32_e32 v7, 0xbe99999a, v7
	v_mul_f32_e32 v8, 0x3fb8aa3b, v7
	v_fma_f32 v9, v7, s8, -v8
	v_rndne_f32_e32 v10, v8
	v_fmac_f32_e32 v9, 0x32a5705f, v7
	v_sub_f32_e32 v8, v8, v10
	v_add_f32_e32 v8, v8, v9
	v_exp_f32_e32 v8, v8
	v_cvt_i32_f32_e32 v9, v10
	s_waitcnt lgkmcnt(0)
	s_add_u32 s48, s42, 0xc000000
	s_addc_u32 s49, s43, 0
	v_mul_f32_e32 v6, 0x3fb8aa3b, v5
	s_add_u32 s59, s42, 0x3000000
	v_ldexp_f32 v8, v8, v9
	v_fma_f32 v9, v5, s8, -v6
	v_rndne_f32_e32 v10, v6
	s_addc_u32 s67, s43, 0
	s_lshl_b32 s40, s70, 7
	v_fmac_f32_e32 v9, 0x32a5705f, v5
	v_sub_f32_e32 v6, v6, v10
	s_lshl_b64 s[6:7], s[40:41], 2
	v_add_f32_e32 v6, v6, v9
	s_add_u32 s56, s12, s6
	s_mov_b32 s6, 0xc2ce8ed0
	v_exp_f32_e32 v6, v6
	v_cvt_i32_f32_e32 v9, v10
	s_addc_u32 s57, s13, s7
	v_cmp_ngt_f32_e32 vcc, s6, v7
	s_mov_b32 s7, 0x42b17218
	v_add_f32_e32 v3, v3, v4
	v_cndmask_b32_e32 v8, 0, v8, vcc
	v_cmp_nlt_f32_e32 vcc, s7, v7
	v_mul_f32_e32 v4, 0x3fb8aa3b, v3
	v_ldexp_f32 v6, v6, v9
	v_cndmask_b32_e32 v7, v196, v8, vcc
	v_mov_b32_e32 v8, 0x3f4ccccd
	v_fmamk_f32 v7, v7, 0xbf19999a, v8
	v_fma_f32 v8, v3, s8, -v4
	v_rndne_f32_e32 v9, v4
	v_fmac_f32_e32 v8, 0x32a5705f, v3
	v_sub_f32_e32 v4, v4, v9
	v_add_f32_e32 v4, v4, v8
	v_exp_f32_e32 v4, v4
	v_cvt_i32_f32_e32 v8, v9
	v_cmp_ngt_f32_e32 vcc, s6, v5
	v_writelane_b32 v255, s70, 16
	v_and_b32_e32 v199, 31, v0
	v_cndmask_b32_e32 v6, 0, v6, vcc
	v_cmp_nlt_f32_e32 vcc, s7, v5
	v_ldexp_f32 v4, v4, v8
	v_bfe_u32 v8, v0, 1, 3
	v_cndmask_b32_e32 v5, v196, v6, vcc
	v_cmp_ngt_f32_e32 vcc, s6, v3
	s_ashr_i32 s6, s1, 6
	s_ashr_i32 s1, s1, 8
	v_cndmask_b32_e32 v4, 0, v4, vcc
	v_cmp_nlt_f32_e32 vcc, s7, v3
	s_lshl_b32 s7, s6, 5
	s_and_b32 s68, s7, 0x60
	v_cndmask_b32_e32 v3, v196, v4, vcc
	s_lshl_b32 s69, s1, 6
	v_sub_f32_e32 v3, v5, v3
	s_add_u32 s70, s42, 0xc000400
	v_add_f32_e32 v170, v7, v3
	v_lshrrev_b32_e32 v3, 5, v1
	s_addc_u32 s71, s43, 0
	s_lshl_b32 s10, s1, 13
	v_lshrrev_b32_e32 v6, 1, v0
	s_cmp_eq_u32 s1, 1
	v_bitop3_b32 v6, v3, v6, 7 bitop3:0x78
	s_cselect_b64 s[60:61], -1, 0
	s_cmp_lt_u32 s6, 4
	v_lshlrev_b32_e32 v201, 4, v6
	v_bitop3_b32 v6, v3, v8, 2 bitop3:0x36
	v_lshrrev_b32_e32 v1, 3, v1
	v_lshlrev_b32_e32 v4, 3, v3
	v_lshlrev_b32_e32 v5, 7, v199
	v_lshlrev_b32_e32 v172, 2, v3
	v_lshlrev_b32_e32 v10, 4, v3
	s_cselect_b64 s[62:63], -1, 0
	v_lshlrev_b32_e32 v202, 4, v6
	v_bitop3_b32 v6, v3, v8, 4 bitop3:0x36
	v_bitop3_b32 v3, v3, v8, 6 bitop3:0x36
	v_lshl_or_b32 v1, s6, 3, v1
	s_movk_i32 s1, 0x600
	s_add_i32 s12, s10, 0x120
	v_lshlrev_b32_e32 v203, 4, v6
	v_lshlrev_b32_e32 v204, 4, v3
	v_lshrrev_b32_e32 v3, 1, v1
	v_mul_lo_u32 v6, v1, s1
	s_lshl_b32 s1, s6, 10
	s_add_i32 s11, s44, 0x120
	v_add_u32_e32 v207, s12, v5
	s_add_i32 s12, s46, 0x120
	v_xor_b32_e32 v3, v3, v0
	s_add_i32 s72, s1, 0x120
	s_add_i32 s52, s11, s1
	s_add_i32 s92, s12, s1
	s_add_i32 s1, s45, 0x120
	v_lshlrev_b32_e32 v3, 3, v3
	v_add_u32_e32 v211, s1, v5
	s_add_i32 s1, s47, 0x120
	v_lshlrev_b32_e32 v0, 5, v0
	v_or_b32_e32 v9, s68, v199
	v_and_b32_e32 v3, 56, v3
	v_lshlrev_b32_e32 v1, 15, v1
	v_add_u32_e32 v212, s1, v5
	s_movk_i32 s1, 0x210
	v_ashrrev_i32_e32 v213, 2, v2
	v_and_b32_e32 v0, 0x60, v0
	v_or_b32_e32 v6, v3, v6
	v_lshl_or_b32 v206, v3, 1, v1
	s_add_i32 s11, s11, s10
	s_add_i32 s12, s12, s10
	v_mad_u32_u24 v1, v9, s1, v195
	v_mul_lo_u32 v2, v213, s1
	v_lshlrev_b32_e32 v3, 2, v0
	s_movk_i32 s1, 0x120
	v_sub_f32_e32 v200, 1.0, v7
	v_lshlrev_b32_e32 v205, 1, v6
	s_add_i32 s73, s72, 0x2000
	s_add_i32 s6, s72, 0x4000
	s_add_i32 s7, s72, 0x6000
	s_add_i32 s8, s72, 0x8000
	s_add_i32 s9, s72, 0xa000
	s_add_i32 s58, s72, 0xc000
	s_add_i32 s79, s72, 0xe000
	s_add_i32 s53, s52, 0x2000
	s_add_i32 s90, s52, 0x4000
	s_add_i32 s91, s52, 0x6000
	s_add_i32 s93, s92, 0x2000
	s_add_i32 s94, s92, 0x4000
	s_add_i32 s95, s92, 0x6000
	v_add_u32_e32 v208, 0x120, v5
	v_add_u32_e32 v209, s11, v5
	v_add_u32_e32 v210, s12, v5
	v_add3_u32 v214, s1, v2, v3
	v_mov_b32_e32 v171, v170
	v_lshlrev_b32_e32 v174, 1, v4
	v_lshlrev_b32_e32 v160, 1, v0
	v_add_u32_e32 v215, v1, v10
	s_mov_b32 s96, s2
	s_branch .LBB0_401

.LBB0_423:
	s_cmp_eq_u32 s100, 1
	s_cbranch_scc1 .Lord_done
	s_mov_b64 s[6:7], s[84:85]
	v_mov_b32_e32 v52, v173
	s_getreg_b32 s1, hwreg(HW_REG_HW_ID, 0, 7)
	s_and_b32 s1, s1, 63
	s_lshl_b32 s1, s1, 2
	v_mov_b32_e32 v0, s1
	ds_read_b32 v0, v0
	s_load_dwordx2 s[10:11], s[6:7], 0xe0
	s_load_dwordx2 s[12:13], s[6:7], 0x10
	s_load_dwordx2 s[16:17], s[6:7], 0x28
	v_readlane_b32 s6, v255, 12
	v_and_b32_e32 v54, 7, v52
	s_waitcnt lgkmcnt(0)
	v_readfirstlane_b32 s1, v0
	s_lshl_b32 s1, s1, 6
	s_and_b32 s1, s1, 0x3fc0
	s_add_u32 s14, s10, 0x7000000
	v_add_u32_e32 v53, s1, v52
	s_addc_u32 s15, s11, 0
	v_readfirstlane_b32 s1, v53
	s_add_u32 s18, s10, 0x4800000
	s_addc_u32 s19, s11, 0
	v_lshrrev_b32_e32 v0, 3, v52
	s_ashr_i32 s1, s1, 3
	v_bfi_b32 v50, -8, s1, v0
	v_readlane_b32 s7, v255, 13
	v_add_u32_e32 v0, 0x200, v53
	v_add_u32_e32 v1, 0x400, v53
	v_add_u32_e32 v2, 0x600, v53
	s_and_b64 vcc, exec, s[6:7]
	v_ashrrev_i32_e32 v99, 4, v53
	v_ashrrev_i32_e32 v51, 31, v50
	v_lshlrev_b32_e32 v48, 11, v54
	v_ashrrev_i32_e32 v118, 4, v0
	v_ashrrev_i32_e32 v119, 4, v1
	v_ashrrev_i32_e32 v120, 4, v2
	s_cbranch_vccnz .LBB0_425
	v_readlane_b32 s6, v254, 50
	s_add_u32 s6, s14, s6
	v_lshlrev_b32_e32 v0, 4, v52
	s_addc_u32 s7, s15, 0
	v_and_b32_e32 v160, 0xf0, v0
	v_readlane_b32 s8, v254, 14
	v_lshl_add_u64 v[28:29], s[6:7], 0, v[160:161]
	v_mov_b32_e32 v49, v161
	v_add_u32_e32 v0, s8, v99
	v_add_u32_e32 v4, s8, v118
	v_mad_i64_i32 v[16:17], s[6:7], v0, s75, v[28:29]
	v_mad_i64_i32 v[20:21], s[6:7], v4, s75, v[28:29]
	global_load_dwordx4 v[0:3], v[16:17], off offset:1024
	global_load_dwordx4 v[8:11], v[16:17], off
	global_load_dwordx4 v[4:7], v[20:21], off offset:1024
	global_load_dwordx4 v[12:15], v[20:21], off offset:2048
	s_nop 0
	global_load_dwordx4 v[16:19], v[16:17], off offset:2048
	s_nop 0
	global_load_dwordx4 v[24:27], v[20:21], off
	v_add_u32_e32 v20, s8, v119
	v_add_u32_e32 v30, s8, v120
	v_mad_i64_i32 v[40:41], s[6:7], v20, s75, v[28:29]
	v_mad_i64_i32 v[44:45], s[6:7], v30, s75, v[28:29]
	v_readlane_b32 s6, v254, 43
	v_readlane_b32 s7, v254, 44
	s_add_u32 s6, s18, s6
	s_addc_u32 s7, s19, s7
	v_lshl_add_u64 v[56:57], v[50:51], 2, s[6:7]
	v_lshl_add_u64 v[56:57], v[56:57], 0, v[48:49]
	global_load_dwordx4 v[20:23], v[40:41], off offset:1024
	global_load_dwordx4 v[32:35], v[40:41], off
	global_load_dwordx4 v[28:31], v[44:45], off offset:1024
	global_load_dwordx4 v[36:39], v[44:45], off offset:2048
	s_nop 0
	global_load_dwordx4 v[40:43], v[40:41], off offset:2048
	s_nop 0
	global_load_dwordx4 v[44:47], v[44:45], off
	s_nop 0
	global_load_dword v86, v[56:57], off
	global_load_dword v87, v[56:57], off offset:256
	global_load_dword v84, v[56:57], off offset:512
	global_load_dword v85, v[56:57], off offset:768
	global_load_dword v82, v[56:57], off offset:1024
	global_load_dword v83, v[56:57], off offset:1280
	global_load_dword v80, v[56:57], off offset:1536
	global_load_dword v81, v[56:57], off offset:1792

.LBB0_504:
	s_cmp_eq_u32 s100, 2
	s_cbranch_scc0 .Lord_done
	s_mov_b32 s100, 1
	s_branch .Lord_att
.Lord_done:
	s_mov_b32 s100, 0
	s_mov_b64 s[10:11], s[84:85]
	v_mov_b32_e32 v0, v173
	s_getreg_b32 s1, hwreg(HW_REG_XCC_ID, 0, 4)
	s_waitcnt vmcnt(0)
	s_barrier
	s_getreg_b32 s6, hwreg(HW_REG_HW_ID, 0, 7)
	s_and_b32 s6, s6, 63
	s_lshl_b32 s6, s6, 2
	v_mov_b32_e32 v1, s6
	ds_read_b32 v1, v1
	v_sub_u32_e32 v0, 0, v0
	s_waitcnt lgkmcnt(0)
	v_readfirstlane_b32 s6, v1
	s_lshl_b32 s6, s6, 6
	s_and_b32 s6, s6, 0x3fc0
	v_cmp_eq_u32_e32 vcc, s6, v0
	s_and_saveexec_b64 s[8:9], vcc
	s_cbranch_execz .LBB0_556
	s_load_dwordx2 s[10:11], s[10:11], 0xe0
	s_waitcnt vmcnt(0) expcnt(0) lgkmcnt(0)
	ds_read_b32 v2, v161 offset:256
	ds_read_b32 v0, v161 offset:260
	s_and_b32 s1, s1, 15
	s_waitcnt lgkmcnt(1)
	v_cmp_ne_u32_e32 vcc, 0, v2
	s_cbranch_vccnz .LBB0_520
	s_add_u32 s12, s10, 0xf500200
	s_addc_u32 s13, s11, 0
	s_add_u32 s14, s10, 0xf500400
	s_addc_u32 s15, s11, 0
	s_add_u32 s16, s10, 0xf500500
	s_addc_u32 s17, s11, 0
	s_add_u32 s18, s10, 0xf500600
	s_addc_u32 s19, s11, 0
	s_add_u32 s20, s10, 0xf500700
	s_addc_u32 s21, s11, 0
	s_add_u32 s22, s10, 0xf500800
	s_addc_u32 s23, s11, 0
	s_add_u32 s24, s10, 0xf500900
	s_addc_u32 s25, s11, 0
	s_add_u32 s26, s10, 0xf500a00
	s_addc_u32 s27, s11, 0
	s_add_u32 s28, s10, 0xf500b00
	s_addc_u32 s29, s11, 0
	s_add_u32 s36, s10, 0xf500c00
	s_addc_u32 s37, s11, 0
	s_add_u32 s38, s10, 0xf500d00
	s_addc_u32 s39, s11, 0
	s_add_u32 s42, s10, 0xf500e00
	s_addc_u32 s43, s11, 0
	s_add_u32 s48, s10, 0xf500f00
	s_addc_u32 s49, s11, 0
	s_add_u32 s56, s10, 0xf501000
	s_addc_u32 s57, s11, 0
	s_add_u32 s60, s10, 0xf501100
	s_addc_u32 s61, s11, 0
	s_add_u32 s62, s10, 0xf501200
	s_addc_u32 s63, s11, 0
	s_add_u32 s66, s10, 0xf501300
	s_addc_u32 s67, s11, 0
	s_mov_b32 s6, 1
	s_branch .LBB0_508
